# EpiResid epilogue: batch 16 base loads before add/store instead of serialized load-wait-store
# speedup vs baseline: 1.0016x; 1.0016x over previous
;     __device__ __forceinline__ void operator()(const f32x4 (&acc)[2][2][4][2], const pg8::Unit& u, int wr, int wc, int fr, int fq) const {
;         const int col0 = u.pn * 256 + wc * 32 + 4 * fq;
; #pragma unroll
;         for (int ai = 0; ai < 2; ++ai)
; #pragma unroll
;             for (int m = 0; m < 4; ++m) {
;                 const size_t off = (size_t)(u.pm * 256 + ai * 128 + wr * 64 + m * 16 + fr) * DM + col0;
; #pragma unroll
;                 for (int bj = 0; bj < 2; ++bj)
; #pragma unroll
;                     for (int n = 0; n < 2; ++n) { const f32x4 b = *(const f32x4*)(base + off + bj * 128 + n * 16); *(f32x4*)(out + off + bj * 128 + n * 16) = b + acc[ai][bj][m][n] * scale; }
;             }
;     }
.LBB0_42:
	s_mov_b64 s[18:19], -1
	s_and_b64 vcc, exec, s[4:5]
	v_lshl_add_u32 v234, s74, 8, v150
	v_lshl_or_b32 v235, s71, 8, v152
	v_lshlrev_b32_e32 v234, 12, v234
	v_lshl_add_u32 v234, v235, 2, v234
	v_add_u32_e32 v236, 0x0, v234
	v_add_u32_e32 v237, 0x10000, v234
	v_add_u32_e32 v238, 0x20000, v234
	v_add_u32_e32 v239, 0x30000, v234
	s_nop 0
	global_load_dwordx4 v[0:3], v236, s[88:89]
	global_load_dwordx4 v[16:19], v236, s[88:89] offset:64
	global_load_dwordx4 v[158:161], v236, s[88:89] offset:512
	global_load_dwordx4 v[162:165], v236, s[88:89] offset:576
	global_load_dwordx4 v[166:169], v237, s[88:89]
	global_load_dwordx4 v[170:173], v237, s[88:89] offset:64
	global_load_dwordx4 v[174:177], v237, s[88:89] offset:512
	global_load_dwordx4 v[178:181], v237, s[88:89] offset:576
	global_load_dwordx4 v[198:201], v238, s[88:89]
	global_load_dwordx4 v[202:205], v238, s[88:89] offset:64
	global_load_dwordx4 v[206:209], v238, s[88:89] offset:512
	global_load_dwordx4 v[210:213], v238, s[88:89] offset:576
	global_load_dwordx4 v[214:217], v239, s[88:89]
	global_load_dwordx4 v[218:221], v239, s[88:89] offset:64
	global_load_dwordx4 v[222:225], v239, s[88:89] offset:512
	global_load_dwordx4 v[226:229], v239, s[88:89] offset:576
	s_waitcnt vmcnt(12)
	v_pk_add_f32 v[2:3], v[146:147], v[2:3]
	v_pk_add_f32 v[0:1], v[148:149], v[0:1]
	global_store_dwordx4 v236, v[0:3], s[88:89]
	v_pk_add_f32 v[18:19], v[138:139], v[18:19]
	v_pk_add_f32 v[16:17], v[140:141], v[16:17]
	global_store_dwordx4 v236, v[16:19], s[88:89] offset:64
	v_pk_add_f32 v[160:161], v[142:143], v[160:161]
	v_pk_add_f32 v[158:159], v[144:145], v[158:159]
	global_store_dwordx4 v236, v[158:161], s[88:89] offset:512
	v_pk_add_f32 v[164:165], v[126:127], v[164:165]
	v_pk_add_f32 v[162:163], v[128:129], v[162:163]
	global_store_dwordx4 v236, v[162:165], s[88:89] offset:576
	s_waitcnt vmcnt(12)
	v_pk_add_f32 v[168:169], v[120:121], v[168:169]
	v_pk_add_f32 v[166:167], v[118:119], v[166:167]
	global_store_dwordx4 v237, v[166:169], s[88:89]
	v_pk_add_f32 v[172:173], v[108:109], v[172:173]
	v_pk_add_f32 v[170:171], v[110:111], v[170:171]
	global_store_dwordx4 v237, v[170:173], s[88:89] offset:64
	v_pk_add_f32 v[176:177], v[114:115], v[176:177]
	v_pk_add_f32 v[174:175], v[116:117], v[174:175]
	global_store_dwordx4 v237, v[174:177], s[88:89] offset:512
	v_pk_add_f32 v[180:181], v[122:123], v[180:181]
	v_pk_add_f32 v[178:179], v[124:125], v[178:179]
	global_store_dwordx4 v237, v[178:181], s[88:89] offset:576
	s_waitcnt vmcnt(12)
	v_pk_add_f32 v[200:201], v[100:101], v[200:201]
	v_pk_add_f32 v[198:199], v[102:103], v[198:199]
	global_store_dwordx4 v238, v[198:201], s[88:89]
	v_pk_add_f32 v[204:205], v[92:93], v[204:205]
	v_pk_add_f32 v[202:203], v[94:95], v[202:203]
	global_store_dwordx4 v238, v[202:205], s[88:89] offset:64
	v_pk_add_f32 v[208:209], v[96:97], v[208:209]
	v_pk_add_f32 v[206:207], v[98:99], v[206:207]
	global_store_dwordx4 v238, v[206:209], s[88:89] offset:512
	v_pk_add_f32 v[212:213], v[104:105], v[212:213]
	v_pk_add_f32 v[210:211], v[106:107], v[210:211]
	global_store_dwordx4 v238, v[210:213], s[88:89] offset:576
	s_waitcnt vmcnt(12)
;     __device__ __forceinline__ void operator()(const f32x4 (&acc)[2][2][4][2], const pg8::Unit& u, int wr, int wc, int fr, int fq) const {
;         const int col0 = u.pn * 256 + wc * 32 + 4 * fq;
; #pragma unroll
;         for (int ai = 0; ai < 2; ++ai)
; #pragma unroll
;             for (int m = 0; m < 4; ++m) {
;                 const size_t off = (size_t)(u.pm * 256 + ai * 128 + wr * 64 + m * 16 + fr) * DM + col0;
; #pragma unroll
;                 for (int bj = 0; bj < 2; ++bj)
; #pragma unroll
;                     for (int n = 0; n < 2; ++n) { const f32x4 b = *(const f32x4*)(base + off + bj * 128 + n * 16); *(f32x4*)(out + off + bj * 128 + n * 16) = b + acc[ai][bj][m][n] * scale; }
;             }
;     }
	v_pk_add_f32 v[216:217], v[84:85], v[216:217]
	v_pk_add_f32 v[214:215], v[86:87], v[214:215]
	global_store_dwordx4 v239, v[214:217], s[88:89]
	v_pk_add_f32 v[220:221], v[76:77], v[220:221]
	v_pk_add_f32 v[218:219], v[78:79], v[218:219]
	global_store_dwordx4 v239, v[218:221], s[88:89] offset:64
	v_pk_add_f32 v[224:225], v[80:81], v[224:225]
	v_pk_add_f32 v[222:223], v[82:83], v[222:223]
	global_store_dwordx4 v239, v[222:225], s[88:89] offset:512
	v_pk_add_f32 v[228:229], v[88:89], v[228:229]
	v_pk_add_f32 v[226:227], v[90:91], v[226:227]
	global_store_dwordx4 v239, v[226:229], s[88:89] offset:576
	v_add_u32_e32 v236, 0x80000, v234
	v_add_u32_e32 v237, 0x90000, v234
	v_add_u32_e32 v238, 0xa0000, v234
	v_add_u32_e32 v239, 0xb0000, v234
	s_nop 0
	global_load_dwordx4 v[0:3], v236, s[88:89]
	global_load_dwordx4 v[16:19], v236, s[88:89] offset:64
	global_load_dwordx4 v[158:161], v236, s[88:89] offset:512
	global_load_dwordx4 v[162:165], v236, s[88:89] offset:576
	global_load_dwordx4 v[166:169], v237, s[88:89]
	global_load_dwordx4 v[170:173], v237, s[88:89] offset:64
	global_load_dwordx4 v[174:177], v237, s[88:89] offset:512
	global_load_dwordx4 v[178:181], v237, s[88:89] offset:576
	global_load_dwordx4 v[198:201], v238, s[88:89]
	global_load_dwordx4 v[202:205], v238, s[88:89] offset:64
	global_load_dwordx4 v[206:209], v238, s[88:89] offset:512
	global_load_dwordx4 v[210:213], v238, s[88:89] offset:576
	global_load_dwordx4 v[214:217], v239, s[88:89]
	global_load_dwordx4 v[218:221], v239, s[88:89] offset:64
	global_load_dwordx4 v[222:225], v239, s[88:89] offset:512
	global_load_dwordx4 v[226:229], v239, s[88:89] offset:576
	s_waitcnt vmcnt(12)
	v_pk_add_f32 v[2:3], v[62:63], v[2:3]
	v_pk_add_f32 v[0:1], v[60:61], v[0:1]
	global_store_dwordx4 v236, v[0:3], s[88:89]
	v_pk_add_f32 v[18:19], v[64:65], v[18:19]
	v_pk_add_f32 v[16:17], v[66:67], v[16:17]
	global_store_dwordx4 v236, v[16:19], s[88:89] offset:64
	v_pk_add_f32 v[160:161], v[68:69], v[160:161]
	v_pk_add_f32 v[158:159], v[70:71], v[158:159]
	global_store_dwordx4 v236, v[158:161], s[88:89] offset:512
	v_pk_add_f32 v[164:165], v[72:73], v[164:165]
	v_pk_add_f32 v[162:163], v[74:75], v[162:163]
	global_store_dwordx4 v236, v[162:165], s[88:89] offset:576
	s_waitcnt vmcnt(12)
	v_pk_add_f32 v[168:169], v[44:45], v[168:169]
	v_pk_add_f32 v[166:167], v[46:47], v[166:167]
	global_store_dwordx4 v237, v[166:169], s[88:89]
	v_pk_add_f32 v[172:173], v[50:51], v[172:173]
	v_pk_add_f32 v[170:171], v[48:49], v[170:171]
	global_store_dwordx4 v237, v[170:173], s[88:89] offset:64
	v_pk_add_f32 v[176:177], v[52:53], v[176:177]
	v_pk_add_f32 v[174:175], v[54:55], v[174:175]
	global_store_dwordx4 v237, v[174:177], s[88:89] offset:512
	v_pk_add_f32 v[180:181], v[56:57], v[180:181]
	v_pk_add_f32 v[178:179], v[58:59], v[178:179]
	global_store_dwordx4 v237, v[178:181], s[88:89] offset:576
	s_waitcnt vmcnt(12)
	v_pk_add_f32 v[200:201], v[28:29], v[200:201]
	v_pk_add_f32 v[198:199], v[30:31], v[198:199]
	global_store_dwordx4 v238, v[198:201], s[88:89]
	v_pk_add_f32 v[204:205], v[34:35], v[204:205]
	v_pk_add_f32 v[202:203], v[32:33], v[202:203]
	global_store_dwordx4 v238, v[202:205], s[88:89] offset:64
	v_pk_add_f32 v[208:209], v[36:37], v[208:209]
	v_pk_add_f32 v[206:207], v[38:39], v[206:207]
	global_store_dwordx4 v238, v[206:209], s[88:89] offset:512
	v_pk_add_f32 v[212:213], v[40:41], v[212:213]
	v_pk_add_f32 v[210:211], v[42:43], v[210:211]
	global_store_dwordx4 v238, v[210:213], s[88:89] offset:576
	s_waitcnt vmcnt(12)
	v_pk_add_f32 v[216:217], v[20:21], v[216:217]
	v_pk_add_f32 v[214:215], v[22:23], v[214:215]
	global_store_dwordx4 v239, v[214:217], s[88:89]
	v_pk_add_f32 v[220:221], v[8:9], v[220:221]
	v_pk_add_f32 v[218:219], v[12:13], v[218:219]
	global_store_dwordx4 v239, v[218:221], s[88:89] offset:64
	v_pk_add_f32 v[224:225], v[10:11], v[224:225]
	v_pk_add_f32 v[222:223], v[14:15], v[222:223]
	global_store_dwordx4 v239, v[222:225], s[88:89] offset:512
	v_pk_add_f32 v[228:229], v[6:7], v[228:229]
	v_pk_add_f32 v[226:227], v[4:5], v[226:227]
	global_store_dwordx4 v239, v[226:229], s[88:89] offset:576
	s_cbranch_vccnz .LBB0_29
	s_andn2_b64 vcc, exec, s[0:1]
	s_cbranch_vccnz .LBB0_28
	s_barrier
	s_branch .LBB0_28

;     __device__ __forceinline__ void operator()(const f32x4 (&acc)[2][2][4][2], const pg8::Unit& u, int wr, int wc, int fr, int fq) const {
;         const int col0 = u.pn * 256 + wc * 32 + 4 * fq;
; #pragma unroll
;         for (int ai = 0; ai < 2; ++ai)
; #pragma unroll
;             for (int m = 0; m < 4; ++m) {
;                 const size_t off = (size_t)(u.pm * 256 + ai * 128 + wr * 64 + m * 16 + fr) * DM + col0;
; #pragma unroll
;                 for (int bj = 0; bj < 2; ++bj)
; #pragma unroll
;                     for (int n = 0; n < 2; ++n) { const f32x4 b = *(const f32x4*)(base + off + bj * 128 + n * 16); *(f32x4*)(out + off + bj * 128 + n * 16) = b + acc[ai][bj][m][n] * scale; }
;             }
;     }
.LBB0_75:
	s_mov_b64 s[20:21], -1
	s_and_b64 vcc, exec, s[4:5]
	v_lshl_add_u32 v226, s77, 8, v140
	v_lshl_or_b32 v227, s75, 8, v142
	v_lshlrev_b32_e32 v226, 12, v226
	v_lshl_add_u32 v226, v227, 2, v226
	v_add_u32_e32 v228, 0x0, v226
	v_add_u32_e32 v229, 0x10000, v226
	v_add_u32_e32 v234, 0x20000, v226
	v_add_u32_e32 v235, 0x30000, v226
	s_nop 0
	global_load_dwordx4 v[136:139], v228, s[88:89]
	global_load_dwordx4 v[144:147], v228, s[88:89] offset:64
	global_load_dwordx4 v[148:151], v228, s[88:89] offset:512
	global_load_dwordx4 v[158:161], v228, s[88:89] offset:576
	global_load_dwordx4 v[162:165], v229, s[88:89]
	global_load_dwordx4 v[166:169], v229, s[88:89] offset:64
	global_load_dwordx4 v[170:173], v229, s[88:89] offset:512
	global_load_dwordx4 v[174:177], v229, s[88:89] offset:576
	global_load_dwordx4 v[178:181], v234, s[88:89]
	global_load_dwordx4 v[198:201], v234, s[88:89] offset:64
	global_load_dwordx4 v[202:205], v234, s[88:89] offset:512
	global_load_dwordx4 v[206:209], v234, s[88:89] offset:576
	global_load_dwordx4 v[210:213], v235, s[88:89]
	global_load_dwordx4 v[214:217], v235, s[88:89] offset:64
	global_load_dwordx4 v[218:221], v235, s[88:89] offset:512
	global_load_dwordx4 v[222:225], v235, s[88:89] offset:576
	s_waitcnt vmcnt(12)
	v_pk_add_f32 v[138:139], v[128:129], v[138:139]
	v_pk_add_f32 v[136:137], v[126:127], v[136:137]
	global_store_dwordx4 v228, v[136:139], s[88:89]
	v_pk_add_f32 v[146:147], v[124:125], v[146:147]
	v_pk_add_f32 v[144:145], v[122:123], v[144:145]
	global_store_dwordx4 v228, v[144:147], s[88:89] offset:64
	v_pk_add_f32 v[150:151], v[120:121], v[150:151]
	v_pk_add_f32 v[148:149], v[118:119], v[148:149]
	global_store_dwordx4 v228, v[148:151], s[88:89] offset:512
	v_pk_add_f32 v[160:161], v[116:117], v[160:161]
	v_pk_add_f32 v[158:159], v[114:115], v[158:159]
	global_store_dwordx4 v228, v[158:161], s[88:89] offset:576
	s_waitcnt vmcnt(12)
	v_pk_add_f32 v[164:165], v[110:111], v[164:165]
	v_pk_add_f32 v[162:163], v[108:109], v[162:163]
	global_store_dwordx4 v229, v[162:165], s[88:89]
	v_pk_add_f32 v[168:169], v[106:107], v[168:169]
	v_pk_add_f32 v[166:167], v[104:105], v[166:167]
	global_store_dwordx4 v229, v[166:169], s[88:89] offset:64
	v_pk_add_f32 v[172:173], v[102:103], v[172:173]
	v_pk_add_f32 v[170:171], v[100:101], v[170:171]
	global_store_dwordx4 v229, v[170:173], s[88:89] offset:512
	v_pk_add_f32 v[176:177], v[98:99], v[176:177]
	v_pk_add_f32 v[174:175], v[96:97], v[174:175]
	global_store_dwordx4 v229, v[174:177], s[88:89] offset:576
	s_waitcnt vmcnt(12)
	v_pk_add_f32 v[180:181], v[94:95], v[180:181]
	v_pk_add_f32 v[178:179], v[92:93], v[178:179]
	global_store_dwordx4 v234, v[178:181], s[88:89]
	v_pk_add_f32 v[200:201], v[90:91], v[200:201]
	v_pk_add_f32 v[198:199], v[88:89], v[198:199]
	global_store_dwordx4 v234, v[198:201], s[88:89] offset:64
	v_pk_add_f32 v[204:205], v[86:87], v[204:205]
	v_pk_add_f32 v[202:203], v[84:85], v[202:203]
	global_store_dwordx4 v234, v[202:205], s[88:89] offset:512
	v_pk_add_f32 v[208:209], v[82:83], v[208:209]
	v_pk_add_f32 v[206:207], v[80:81], v[206:207]
	global_store_dwordx4 v234, v[206:209], s[88:89] offset:576
	s_waitcnt vmcnt(12)
;     __device__ __forceinline__ void operator()(const f32x4 (&acc)[2][2][4][2], const pg8::Unit& u, int wr, int wc, int fr, int fq) const {
;         const int col0 = u.pn * 256 + wc * 32 + 4 * fq;
; #pragma unroll
;         for (int ai = 0; ai < 2; ++ai)
; #pragma unroll
;             for (int m = 0; m < 4; ++m) {
;                 const size_t off = (size_t)(u.pm * 256 + ai * 128 + wr * 64 + m * 16 + fr) * DM + col0;
; #pragma unroll
;                 for (int bj = 0; bj < 2; ++bj)
; #pragma unroll
;                     for (int n = 0; n < 2; ++n) { const f32x4 b = *(const f32x4*)(base + off + bj * 128 + n * 16); *(f32x4*)(out + off + bj * 128 + n * 16) = b + acc[ai][bj][m][n] * scale; }
;             }
;     }
	v_pk_add_f32 v[212:213], v[78:79], v[212:213]
	v_pk_add_f32 v[210:211], v[76:77], v[210:211]
	global_store_dwordx4 v235, v[210:213], s[88:89]
	v_pk_add_f32 v[216:217], v[74:75], v[216:217]
	v_pk_add_f32 v[214:215], v[72:73], v[214:215]
	global_store_dwordx4 v235, v[214:217], s[88:89] offset:64
	v_pk_add_f32 v[220:221], v[70:71], v[220:221]
	v_pk_add_f32 v[218:219], v[68:69], v[218:219]
	global_store_dwordx4 v235, v[218:221], s[88:89] offset:512
	v_pk_add_f32 v[224:225], v[66:67], v[224:225]
	v_pk_add_f32 v[222:223], v[64:65], v[222:223]
	global_store_dwordx4 v235, v[222:225], s[88:89] offset:576
	v_add_u32_e32 v228, 0x80000, v226
	v_add_u32_e32 v229, 0x90000, v226
	v_add_u32_e32 v234, 0xa0000, v226
	v_add_u32_e32 v235, 0xb0000, v226
	s_nop 0
	global_load_dwordx4 v[136:139], v228, s[88:89]
	global_load_dwordx4 v[144:147], v228, s[88:89] offset:64
	global_load_dwordx4 v[148:151], v228, s[88:89] offset:512
	global_load_dwordx4 v[158:161], v228, s[88:89] offset:576
	global_load_dwordx4 v[162:165], v229, s[88:89]
	global_load_dwordx4 v[166:169], v229, s[88:89] offset:64
	global_load_dwordx4 v[170:173], v229, s[88:89] offset:512
	global_load_dwordx4 v[174:177], v229, s[88:89] offset:576
	global_load_dwordx4 v[178:181], v234, s[88:89]
	global_load_dwordx4 v[198:201], v234, s[88:89] offset:64
	global_load_dwordx4 v[202:205], v234, s[88:89] offset:512
	global_load_dwordx4 v[206:209], v234, s[88:89] offset:576
	global_load_dwordx4 v[210:213], v235, s[88:89]
	global_load_dwordx4 v[214:217], v235, s[88:89] offset:64
	global_load_dwordx4 v[218:221], v235, s[88:89] offset:512
	global_load_dwordx4 v[222:225], v235, s[88:89] offset:576
	s_waitcnt vmcnt(12)
	v_pk_add_f32 v[138:139], v[62:63], v[138:139]
	v_pk_add_f32 v[136:137], v[60:61], v[136:137]
	global_store_dwordx4 v228, v[136:139], s[88:89]
	v_pk_add_f32 v[146:147], v[58:59], v[146:147]
	v_pk_add_f32 v[144:145], v[56:57], v[144:145]
	global_store_dwordx4 v228, v[144:147], s[88:89] offset:64
	v_pk_add_f32 v[150:151], v[54:55], v[150:151]
	v_pk_add_f32 v[148:149], v[52:53], v[148:149]
	global_store_dwordx4 v228, v[148:151], s[88:89] offset:512
	v_pk_add_f32 v[160:161], v[50:51], v[160:161]
	v_pk_add_f32 v[158:159], v[48:49], v[158:159]
	global_store_dwordx4 v228, v[158:161], s[88:89] offset:576
	s_waitcnt vmcnt(12)
	v_pk_add_f32 v[164:165], v[46:47], v[164:165]
	v_pk_add_f32 v[162:163], v[44:45], v[162:163]
	global_store_dwordx4 v229, v[162:165], s[88:89]
	v_pk_add_f32 v[168:169], v[42:43], v[168:169]
	v_pk_add_f32 v[166:167], v[40:41], v[166:167]
	global_store_dwordx4 v229, v[166:169], s[88:89] offset:64
	v_pk_add_f32 v[172:173], v[38:39], v[172:173]
	v_pk_add_f32 v[170:171], v[36:37], v[170:171]
	global_store_dwordx4 v229, v[170:173], s[88:89] offset:512
	v_pk_add_f32 v[176:177], v[34:35], v[176:177]
	v_pk_add_f32 v[174:175], v[32:33], v[174:175]
	global_store_dwordx4 v229, v[174:177], s[88:89] offset:576
	s_waitcnt vmcnt(12)
	v_pk_add_f32 v[180:181], v[30:31], v[180:181]
	v_pk_add_f32 v[178:179], v[28:29], v[178:179]
	global_store_dwordx4 v234, v[178:181], s[88:89]
	v_pk_add_f32 v[200:201], v[26:27], v[200:201]
	v_pk_add_f32 v[198:199], v[24:25], v[198:199]
	global_store_dwordx4 v234, v[198:201], s[88:89] offset:64
	v_pk_add_f32 v[204:205], v[22:23], v[204:205]
	v_pk_add_f32 v[202:203], v[20:21], v[202:203]
	global_store_dwordx4 v234, v[202:205], s[88:89] offset:512
	v_pk_add_f32 v[208:209], v[18:19], v[208:209]
	v_pk_add_f32 v[206:207], v[16:17], v[206:207]
	global_store_dwordx4 v234, v[206:209], s[88:89] offset:576
	s_waitcnt vmcnt(12)
	v_pk_add_f32 v[212:213], v[14:15], v[212:213]
	v_pk_add_f32 v[210:211], v[12:13], v[210:211]
	global_store_dwordx4 v235, v[210:213], s[88:89]
	v_pk_add_f32 v[216:217], v[10:11], v[216:217]
	v_pk_add_f32 v[214:215], v[8:9], v[214:215]
	global_store_dwordx4 v235, v[214:217], s[88:89] offset:64
	v_pk_add_f32 v[220:221], v[6:7], v[220:221]
	v_pk_add_f32 v[218:219], v[4:5], v[218:219]
	global_store_dwordx4 v235, v[218:221], s[88:89] offset:512
	v_pk_add_f32 v[224:225], v[2:3], v[224:225]
	v_pk_add_f32 v[222:223], v[0:1], v[222:223]
	global_store_dwordx4 v235, v[222:225], s[88:89] offset:576
	s_cbranch_vccnz .LBB0_63
	s_andn2_b64 vcc, exec, s[0:1]
	s_cbranch_vccnz .LBB0_62
	s_barrier
	s_branch .LBB0_62

;     __device__ __forceinline__ void operator()(const f32x4 (&acc)[2][2][4][2], const pg8::Unit& u, int wr, int wc, int fr, int fq) const {
;         const int col0 = u.pn * 256 + wc * 32 + 4 * fq;
; #pragma unroll
;         for (int ai = 0; ai < 2; ++ai)
; #pragma unroll
;             for (int m = 0; m < 4; ++m) {
;                 const size_t off = (size_t)(u.pm * 256 + ai * 128 + wr * 64 + m * 16 + fr) * DM + col0;
; #pragma unroll
;                 for (int bj = 0; bj < 2; ++bj)
; #pragma unroll
;                     for (int n = 0; n < 2; ++n) { const f32x4 b = *(const f32x4*)(base + off + bj * 128 + n * 16); *(f32x4*)(out + off + bj * 128 + n * 16) = b + acc[ai][bj][m][n] * scale; }
;             }
;     }
.LBB0_758:
	v_readlane_b32 s20, v255, 12
	v_readlane_b32 s21, v255, 13
	s_and_b64 vcc, exec, s[4:5]
	s_mov_b64 s[4:5], -1
	v_lshl_add_u32 v226, s76, 8, v148
	v_lshl_or_b32 v227, s75, 8, v150
	v_lshlrev_b32_e32 v226, 12, v226
	v_lshl_add_u32 v226, v227, 2, v226
	v_add_u32_e32 v228, 0x0, v226
	v_add_u32_e32 v229, 0x10000, v226
	v_add_u32_e32 v234, 0x20000, v226
	v_add_u32_e32 v235, 0x30000, v226
	s_nop 0
	global_load_dwordx4 v[16:19], v228, s[20:21]
	global_load_dwordx4 v[24:27], v228, s[20:21] offset:64
	global_load_dwordx4 v[40:43], v228, s[20:21] offset:512
	global_load_dwordx4 v[158:161], v228, s[20:21] offset:576
	global_load_dwordx4 v[162:165], v229, s[20:21]
	global_load_dwordx4 v[166:169], v229, s[20:21] offset:64
	global_load_dwordx4 v[170:173], v229, s[20:21] offset:512
	global_load_dwordx4 v[174:177], v229, s[20:21] offset:576
	global_load_dwordx4 v[178:181], v234, s[20:21]
	global_load_dwordx4 v[198:201], v234, s[20:21] offset:64
	global_load_dwordx4 v[202:205], v234, s[20:21] offset:512
	global_load_dwordx4 v[206:209], v234, s[20:21] offset:576
	global_load_dwordx4 v[210:213], v235, s[20:21]
	global_load_dwordx4 v[214:217], v235, s[20:21] offset:64
	global_load_dwordx4 v[218:221], v235, s[20:21] offset:512
	global_load_dwordx4 v[222:225], v235, s[20:21] offset:576
	s_waitcnt vmcnt(12)
	v_pk_add_f32 v[18:19], v[140:141], v[18:19]
	v_pk_add_f32 v[16:17], v[142:143], v[16:17]
	global_store_dwordx4 v228, v[16:19], s[88:89]
	v_pk_add_f32 v[26:27], v[138:139], v[26:27]
	v_pk_add_f32 v[24:25], v[136:137], v[24:25]
	global_store_dwordx4 v228, v[24:27], s[88:89] offset:64
	v_pk_add_f32 v[42:43], v[146:147], v[42:43]
	v_pk_add_f32 v[40:41], v[144:145], v[40:41]
	global_store_dwordx4 v228, v[40:43], s[88:89] offset:512
	v_pk_add_f32 v[160:161], v[126:127], v[160:161]
	v_pk_add_f32 v[158:159], v[128:129], v[158:159]
	global_store_dwordx4 v228, v[158:161], s[88:89] offset:576
	s_waitcnt vmcnt(12)
	v_pk_add_f32 v[164:165], v[120:121], v[164:165]
	v_pk_add_f32 v[162:163], v[118:119], v[162:163]
	global_store_dwordx4 v229, v[162:165], s[88:89]
	v_pk_add_f32 v[168:169], v[116:117], v[168:169]
	v_pk_add_f32 v[166:167], v[114:115], v[166:167]
	global_store_dwordx4 v229, v[166:169], s[88:89] offset:64
	v_pk_add_f32 v[172:173], v[124:125], v[172:173]
	v_pk_add_f32 v[170:171], v[122:123], v[170:171]
	global_store_dwordx4 v229, v[170:173], s[88:89] offset:512
	v_pk_add_f32 v[176:177], v[108:109], v[176:177]
	v_pk_add_f32 v[174:175], v[110:111], v[174:175]
	global_store_dwordx4 v229, v[174:177], s[88:89] offset:576
	s_waitcnt vmcnt(12)
	v_pk_add_f32 v[180:181], v[100:101], v[180:181]
	v_pk_add_f32 v[178:179], v[102:103], v[178:179]
	global_store_dwordx4 v234, v[178:181], s[88:89]
	v_pk_add_f32 v[200:201], v[98:99], v[200:201]
	v_pk_add_f32 v[198:199], v[96:97], v[198:199]
	global_store_dwordx4 v234, v[198:201], s[88:89] offset:64
	v_pk_add_f32 v[204:205], v[106:107], v[204:205]
	v_pk_add_f32 v[202:203], v[104:105], v[202:203]
	global_store_dwordx4 v234, v[202:205], s[88:89] offset:512
	v_pk_add_f32 v[208:209], v[92:93], v[208:209]
	v_pk_add_f32 v[206:207], v[94:95], v[206:207]
	global_store_dwordx4 v234, v[206:209], s[88:89] offset:576
	s_waitcnt vmcnt(12)
;     __device__ __forceinline__ void operator()(const f32x4 (&acc)[2][2][4][2], const pg8::Unit& u, int wr, int wc, int fr, int fq) const {
;         const int col0 = u.pn * 256 + wc * 32 + 4 * fq;
; #pragma unroll
;         for (int ai = 0; ai < 2; ++ai)
; #pragma unroll
;             for (int m = 0; m < 4; ++m) {
;                 const size_t off = (size_t)(u.pm * 256 + ai * 128 + wr * 64 + m * 16 + fr) * DM + col0;
; #pragma unroll
;                 for (int bj = 0; bj < 2; ++bj)
; #pragma unroll
;                     for (int n = 0; n < 2; ++n) { const f32x4 b = *(const f32x4*)(base + off + bj * 128 + n * 16); *(f32x4*)(out + off + bj * 128 + n * 16) = b + acc[ai][bj][m][n] * scale; }
;             }
;     }
	v_pk_add_f32 v[212:213], v[84:85], v[212:213]
	v_pk_add_f32 v[210:211], v[86:87], v[210:211]
	global_store_dwordx4 v235, v[210:213], s[88:89]
	v_pk_add_f32 v[216:217], v[78:79], v[216:217]
	v_pk_add_f32 v[214:215], v[76:77], v[214:215]
	global_store_dwordx4 v235, v[214:217], s[88:89] offset:64
	v_pk_add_f32 v[220:221], v[90:91], v[220:221]
	v_pk_add_f32 v[218:219], v[88:89], v[218:219]
	global_store_dwordx4 v235, v[218:221], s[88:89] offset:512
	v_pk_add_f32 v[224:225], v[72:73], v[224:225]
	v_pk_add_f32 v[222:223], v[74:75], v[222:223]
	global_store_dwordx4 v235, v[222:225], s[88:89] offset:576
	v_add_u32_e32 v228, 0x80000, v226
	v_add_u32_e32 v229, 0x90000, v226
	v_add_u32_e32 v234, 0xa0000, v226
	v_add_u32_e32 v235, 0xb0000, v226
	s_nop 0
	global_load_dwordx4 v[16:19], v228, s[20:21]
	global_load_dwordx4 v[24:27], v228, s[20:21] offset:64
	global_load_dwordx4 v[40:43], v228, s[20:21] offset:512
	global_load_dwordx4 v[158:161], v228, s[20:21] offset:576
	global_load_dwordx4 v[162:165], v229, s[20:21]
	global_load_dwordx4 v[166:169], v229, s[20:21] offset:64
	global_load_dwordx4 v[170:173], v229, s[20:21] offset:512
	global_load_dwordx4 v[174:177], v229, s[20:21] offset:576
	global_load_dwordx4 v[178:181], v234, s[20:21]
	global_load_dwordx4 v[198:201], v234, s[20:21] offset:64
	global_load_dwordx4 v[202:205], v234, s[20:21] offset:512
	global_load_dwordx4 v[206:209], v234, s[20:21] offset:576
	global_load_dwordx4 v[210:213], v235, s[20:21]
	global_load_dwordx4 v[214:217], v235, s[20:21] offset:64
	global_load_dwordx4 v[218:221], v235, s[20:21] offset:512
	global_load_dwordx4 v[222:225], v235, s[20:21] offset:576
	s_waitcnt vmcnt(12)
	v_pk_add_f32 v[18:19], v[68:69], v[18:19]
	v_pk_add_f32 v[16:17], v[70:71], v[16:17]
	global_store_dwordx4 v228, v[16:19], s[88:89]
	v_pk_add_f32 v[26:27], v[66:67], v[26:27]
	v_pk_add_f32 v[24:25], v[64:65], v[24:25]
	global_store_dwordx4 v228, v[24:27], s[88:89] offset:64
	v_pk_add_f32 v[42:43], v[82:83], v[42:43]
	v_pk_add_f32 v[40:41], v[80:81], v[40:41]
	global_store_dwordx4 v228, v[40:43], s[88:89] offset:512
	v_pk_add_f32 v[160:161], v[60:61], v[160:161]
	v_pk_add_f32 v[158:159], v[62:63], v[158:159]
	global_store_dwordx4 v228, v[158:161], s[88:89] offset:576
	s_waitcnt vmcnt(12)
	v_pk_add_f32 v[164:165], v[54:55], v[164:165]
	v_pk_add_f32 v[162:163], v[52:53], v[162:163]
	global_store_dwordx4 v229, v[162:165], s[88:89]
	v_pk_add_f32 v[168:169], v[50:51], v[168:169]
	v_pk_add_f32 v[166:167], v[48:49], v[166:167]
	global_store_dwordx4 v229, v[166:169], s[88:89] offset:64
	v_pk_add_f32 v[172:173], v[58:59], v[172:173]
	v_pk_add_f32 v[170:171], v[56:57], v[170:171]
	global_store_dwordx4 v229, v[170:173], s[88:89] offset:512
	v_pk_add_f32 v[176:177], v[44:45], v[176:177]
	v_pk_add_f32 v[174:175], v[46:47], v[174:175]
	global_store_dwordx4 v229, v[174:177], s[88:89] offset:576
	s_waitcnt vmcnt(12)
	v_pk_add_f32 v[180:181], v[36:37], v[180:181]
	v_pk_add_f32 v[178:179], v[38:39], v[178:179]
	global_store_dwordx4 v234, v[178:181], s[88:89]
	v_pk_add_f32 v[200:201], v[30:31], v[200:201]
	v_pk_add_f32 v[198:199], v[28:29], v[198:199]
	global_store_dwordx4 v234, v[198:201], s[88:89] offset:64
	v_pk_add_f32 v[204:205], v[34:35], v[204:205]
	v_pk_add_f32 v[202:203], v[32:33], v[202:203]
	global_store_dwordx4 v234, v[202:205], s[88:89] offset:512
	v_pk_add_f32 v[208:209], v[20:21], v[208:209]
	v_pk_add_f32 v[206:207], v[22:23], v[206:207]
	global_store_dwordx4 v234, v[206:209], s[88:89] offset:576
	s_waitcnt vmcnt(12)
	v_pk_add_f32 v[212:213], v[12:13], v[212:213]
	v_pk_add_f32 v[210:211], v[14:15], v[210:211]
	global_store_dwordx4 v235, v[210:213], s[88:89]
	v_pk_add_f32 v[216:217], v[10:11], v[216:217]
	v_pk_add_f32 v[214:215], v[8:9], v[214:215]
	global_store_dwordx4 v235, v[214:217], s[88:89] offset:64
	v_pk_add_f32 v[220:221], v[6:7], v[220:221]
	v_pk_add_f32 v[218:219], v[4:5], v[218:219]
	global_store_dwordx4 v235, v[218:221], s[88:89] offset:512
	v_pk_add_f32 v[224:225], v[2:3], v[224:225]
	v_pk_add_f32 v[222:223], v[0:1], v[222:223]
	global_store_dwordx4 v235, v[222:225], s[88:89] offset:576
	s_cbranch_vccnz .LBB0_745
	s_andn2_b64 vcc, exec, s[12:13]
	s_cbranch_vccnz .LBB0_744
	s_barrier
	s_branch .LBB0_744
